# prologue x->bf16 row loop: next row's loads issued while the current row is reduced and stored (register double buffer)
# speedup vs baseline: 1.0025x; 1.0025x over previous
; DI unsigned pk2(float lo, float hi) { f32x2 v = {lo, hi}; bf16x2_t b = __builtin_convertvector(v, bf16x2_t); return __builtin_bit_cast(unsigned, b); }
; DI void phase_prologue(const Params& p, unsigned char* lds) {
;     ...
;   for (long row = (long)blockIdx.x * 8 + (tid >> 6); row < NTOK; row += (long)gridDim.x * 8) {
;     const float* xr = p.x_in + row * D_MODEL; bf16_t* xo = p.xb() + row * LDX;
;     float ss = 0.f;
; #pragma unroll
;     for (int u = 0; u < 4; ++u) {
;       const f32x4 v = *(const f32x4*)(xr + u * 256 + lane * 4);
;       ss += v[0] * v[0] + v[1] * v[1] + v[2] * v[2] + v[3] * v[3];
;       *(u32x2*)(xo + u * 256 + lane * 4) = (u32x2){pk2(v[0], v[1]), pk2(v[2], v[3])};
;     }
; #pragma unroll
;     for (int o = 32; o >= 1; o >>= 1) ss += __shfl_xor(ss, o);
;     if (lane < 8) p.part()[row * 16 + lane] = lane == 0 ? ss : 0.f;
;   }
.LBB0_158:
	s_or_b64 exec, exec, s[10:11]
	v_ashrrev_i32_e32 v7, 31, v6
	v_lshl_add_u64 v[2:3], s[96:97], 3, v[6:7]
	s_mov_b64 s[0:1], 0x8000
	v_cmp_gt_i64_e32 vcc, s[0:1], v[2:3]
	v_mbcnt_lo_u32_b32 v12, -1, 0
	s_and_saveexec_b64 s[14:15], vcc
	s_cbranch_execz .LBB0_163
	v_mbcnt_hi_u32_b32 v8, -1, v12
	v_and_b32_e32 v9, 64, v8
	v_add_u32_e32 v9, 64, v9
	v_xor_b32_e32 v10, 32, v8
	v_cmp_lt_i32_e64 s[0:1], v10, v9
	v_mov_b32_e32 v5, 0
	v_readlane_b32 s36, v253, 8
	v_cndmask_b32_e64 v10, v8, v10, s[0:1]
	v_lshlrev_b32_e32 v13, 2, v10
	v_xor_b32_e32 v10, 16, v8
	v_cmp_lt_i32_e64 s[0:1], v10, v9
	v_readlane_b32 s37, v253, 9
	v_cmp_gt_u32_e32 vcc, 8, v1
	v_cndmask_b32_e64 v10, v8, v10, s[0:1]
	v_lshlrev_b32_e32 v14, 2, v10
	v_xor_b32_e32 v10, 8, v8
	v_cmp_lt_i32_e64 s[0:1], v10, v9
	v_cmp_eq_u32_e64 s[10:11], 0, v1
	s_lshl_b64 s[16:17], s[6:7], 3
	v_cndmask_b32_e64 v10, v8, v10, s[0:1]
	v_lshlrev_b32_e32 v15, 2, v10
	v_xor_b32_e32 v10, 4, v8
	v_cmp_lt_i32_e64 s[0:1], v10, v9
	s_mov_b64 s[18:19], 0
	s_mov_b64 s[20:21], 0x7fff
	v_cndmask_b32_e64 v10, v8, v10, s[0:1]
	v_lshlrev_b32_e32 v16, 2, v10
	v_xor_b32_e32 v10, 2, v8
	v_cmp_lt_i32_e64 s[0:1], v10, v9
	v_readlane_b32 s38, v253, 10
	v_readlane_b32 s39, v253, 11
	v_cndmask_b32_e64 v10, v8, v10, s[0:1]
	v_lshlrev_b32_e32 v17, 2, v10
	v_xor_b32_e32 v10, 1, v8
	v_cmp_lt_i32_e64 s[0:1], v10, v9
	v_readlane_b32 s40, v253, 12
	v_readlane_b32 s41, v253, 13
	v_cndmask_b32_e64 v8, v8, v10, s[0:1]
	v_lshlrev_b32_e32 v18, 2, v8
	v_lshlrev_b64 v[8:9], 6, v[6:7]
	v_lshl_add_u64 v[8:9], s[12:13], 0, v[8:9]
	v_lshl_add_u64 v[8:9], v[8:9], 0, v[4:5]
	v_lshl_add_u64 v[8:9], s[92:93], 0, v[8:9]
	s_mov_b64 s[0:1], 0x5f70000
	v_lshl_add_u64 v[8:9], v[8:9], 0, s[0:1]
	s_lshl_b64 s[0:1], s[96:97], 15
	v_lshlrev_b64 v[10:11], 12, v[6:7]
	v_lshl_add_u64 v[10:11], s[0:1], 0, v[10:11]
	v_lshl_or_b32 v10, v1, 4, v10
	v_lshl_add_u64 v[10:11], s[36:37], 0, v[10:11]
	s_mov_b64 s[0:1], 0x800
	v_lshl_add_u64 v[10:11], v[10:11], 0, s[0:1]
	s_movk_i32 s0, 0x880
	v_mad_i64_i32 v[6:7], s[0:1], v6, s0, 0
	v_mov_b32_e32 v4, 0x4400
	v_mad_u64_u32 v[6:7], s[0:1], s96, v4, v[6:7]
	v_lshlrev_b32_e32 v4, 3, v1
	v_lshl_add_u64 v[4:5], v[6:7], 0, v[4:5]
	v_lshl_add_u64 v[4:5], s[92:93], 0, v[4:5]
	s_mov_b64 s[0:1], 0x1b70400
	s_lshl_b64 s[12:13], s[6:7], 15
	v_lshl_add_u64 v[4:5], v[4:5], 0, s[0:1]
	s_mul_hi_u32 s7, s6, 0x4400
	s_mulk_i32 s6, 0x4400
	v_readlane_b32 s42, v253, 14
	v_readlane_b32 s43, v253, 15
	v_readlane_b32 s44, v253, 16
	v_readlane_b32 s45, v253, 17
	v_readlane_b32 s46, v253, 18
	v_readlane_b32 s47, v253, 19
	v_readlane_b32 s48, v253, 20
	v_readlane_b32 s49, v253, 21
	v_readlane_b32 s50, v253, 22
	v_readlane_b32 s51, v253, 23
	global_load_dwordx4 v[36:39], v[10:11], off offset:-2048
	global_load_dwordx4 v[40:43], v[10:11], off offset:-1024
	global_load_dwordx4 v[44:47], v[10:11], off
	global_load_dwordx4 v[48:51], v[10:11], off offset:1024
	s_waitcnt vmcnt(0)
	s_branch .LBB0_161
.LBB0_160:
	s_or_b64 exec, exec, s[0:1]
	s_waitcnt vmcnt(4)
	v_lshl_add_u64 v[2:3], v[2:3], 0, s[16:17]
	v_cmp_lt_i64_e64 s[0:1], s[20:21], v[2:3]
	v_lshl_add_u64 v[8:9], v[8:9], 0, s[4:5]
	v_lshl_add_u64 v[10:11], v[10:11], 0, s[12:13]
	s_or_b64 s[18:19], s[0:1], s[18:19]
	v_lshl_add_u64 v[4:5], v[4:5], 0, s[6:7]
	s_andn2_b64 exec, exec, s[18:19]
	s_cbranch_execz .LBB0_163
.LBB0_161:
	v_mov_b64_e32 v[20:21], v[36:37]
	v_mov_b64_e32 v[22:23], v[38:39]
	v_mov_b64_e32 v[24:25], v[40:41]
	v_mov_b64_e32 v[26:27], v[42:43]
	v_mov_b64_e32 v[28:29], v[44:45]
	v_mov_b64_e32 v[30:31], v[46:47]
	v_mov_b64_e32 v[32:33], v[48:49]
	v_mov_b64_e32 v[34:35], v[50:51]
	v_lshl_add_u64 v[52:53], v[2:3], 0, s[16:17]
	v_cmp_ge_i64_e64 s[26:27], s[20:21], v[52:53]
	s_and_saveexec_b64 s[28:29], s[26:27]
	v_lshl_add_u64 v[52:53], v[10:11], 0, s[12:13]
	global_load_dwordx4 v[36:39], v[52:53], off offset:-2048
	global_load_dwordx4 v[40:43], v[52:53], off offset:-1024
	global_load_dwordx4 v[44:47], v[52:53], off
	global_load_dwordx4 v[48:51], v[52:53], off offset:1024
	s_mov_b64 exec, s[28:29]
	s_waitcnt lgkmcnt(0)
	v_cvt_pk_bf16_f32 v6, v20, v21
	v_cvt_pk_bf16_f32 v7, v22, v23
	global_store_dwordx2 v[4:5], v[6:7], off offset:-1024
	v_mul_f32_e32 v1, v21, v21
	v_fmac_f32_e32 v1, v20, v20
	v_fmac_f32_e32 v1, v22, v22
	v_fmac_f32_e32 v1, v23, v23
	v_cvt_pk_bf16_f32 v6, v24, v25
	v_cvt_pk_bf16_f32 v7, v26, v27
	global_store_dwordx2 v[4:5], v[6:7], off offset:-512
	v_cvt_pk_bf16_f32 v6, v28, v29
	v_cvt_pk_bf16_f32 v7, v30, v31
	global_store_dwordx2 v[4:5], v[6:7], off
	v_mul_f32_e32 v6, v25, v25
	v_fmac_f32_e32 v6, v24, v24
	v_fmac_f32_e32 v6, v26, v26
	v_fmac_f32_e32 v6, v27, v27
	v_add_f32_e32 v1, v1, v6
	v_mul_f32_e32 v6, v29, v29
	v_fmac_f32_e32 v6, v28, v28
	v_fmac_f32_e32 v6, v30, v30
	v_fmac_f32_e32 v6, v31, v31
	v_add_f32_e32 v1, v1, v6
	v_mul_f32_e32 v6, v33, v33
	v_fmac_f32_e32 v6, v32, v32
	v_fmac_f32_e32 v6, v34, v34
	v_fmac_f32_e32 v6, v35, v35
	v_add_f32_e32 v1, v1, v6
	ds_bpermute_b32 v6, v13, v1
	v_cvt_pk_bf16_f32 v20, v32, v33
	v_cvt_pk_bf16_f32 v21, v34, v35
	global_store_dwordx2 v[4:5], v[20:21], off offset:512
	s_waitcnt lgkmcnt(0)
	v_add_f32_e32 v1, v1, v6
	ds_bpermute_b32 v6, v14, v1
	s_waitcnt lgkmcnt(0)
	v_add_f32_e32 v1, v1, v6
	ds_bpermute_b32 v6, v15, v1
	s_waitcnt lgkmcnt(0)
	v_add_f32_e32 v1, v1, v6
	ds_bpermute_b32 v6, v16, v1
	s_waitcnt lgkmcnt(0)
	v_add_f32_e32 v1, v1, v6
	ds_bpermute_b32 v6, v17, v1
	s_waitcnt lgkmcnt(0)
	v_add_f32_e32 v1, v1, v6
	ds_bpermute_b32 v6, v18, v1
	s_and_saveexec_b64 s[0:1], vcc
	s_cbranch_execz .LBB0_160
	s_waitcnt lgkmcnt(0)
	v_add_f32_e32 v1, v1, v6
	v_cndmask_b32_e64 v1, 0, v1, s[10:11]
	global_store_dword v[8:9], v1, off
	s_branch .LBB0_160
